# diff-attn fast loop PV head reordered: first V fragment reads hoisted above the exps, c0 P ready first so PV MFMA 1 issues ~90 cycles earlier (exp dst renamed to v240), lgkmcnt waits re-derived
# baseline (speedup 1.0000x reference)
.Lfast_loop:
	s_waitcnt vmcnt(0)
	s_barrier
	s_add_u32 s80, s74, s42
	s_addc_u32 s81, s75, s43
	s_add_i32 s4, s55, 0x8000
	s_mov_b32 m0, s4
	s_add_u32 s82, s76, s42
	s_addc_u32 s83, s77, s43
	global_load_lds_dwordx4 v254, s[80:81]
	s_add_i32 m0, s4, 0x1f80
	s_add_u32 s84, s82, 0x54000
	s_addc_u32 s85, s83, 0
	global_load_lds_dwordx4 v254, s[80:81] offset:128
	s_add_i32 m0, s4, 0x4000
	s_nop 0
	global_load_lds_dwordx4 v255, s[82:83]
	s_add_i32 m0, s4, 0x6000
	s_nop 0
	global_load_lds_dwordx4 v255, s[84:85]
	ds_read_b128 v[6:9], v236
	ds_read_b128 v[178:181], v226
	ds_read_b128 v[182:185], v226 offset:4096
	ds_read_b128 v[10:13], v236 offset:32
	ds_read_b128 v[186:189], v227
	ds_read_b128 v[190:193], v227 offset:4096
	ds_read_b128 v[14:17], v236 offset:64
	ds_read_b128 v[194:197], v228
	ds_read_b128 v[198:201], v228 offset:4096
	ds_read_b128 v[238:241], v236 offset:96
	ds_read_b128 v[202:205], v230
	ds_read_b128 v[206:209], v230 offset:4096
	s_waitcnt lgkmcnt(10)
	v_mfma_f32_32x32x16_bf16 v[162:177], v[178:181], v[6:9], 0
	s_waitcnt lgkmcnt(9)
	v_mfma_f32_32x32x16_bf16 v[146:161], v[182:185], v[6:9], 0
	ds_read_b128 v[246:249], v236 offset:128
	ds_read_b128 v[250:253], v226 offset:8192
	ds_read_b128 v[6:9], v226 offset:12288
	s_waitcnt lgkmcnt(10)
	v_mfma_f32_32x32x16_bf16 v[162:177], v[186:189], v[10:13], v[162:177]
	s_waitcnt lgkmcnt(9)
	v_mfma_f32_32x32x16_bf16 v[146:161], v[190:193], v[10:13], v[146:161]
	ds_read_b128 v[10:13], v236 offset:160
	s_waitcnt lgkmcnt(8)
	v_mfma_f32_32x32x16_bf16 v[162:177], v[194:197], v[14:17], v[162:177]
	s_waitcnt lgkmcnt(7)
	v_mfma_f32_32x32x16_bf16 v[146:161], v[198:201], v[14:17], v[146:161]
	ds_read_b128 v[14:17], v227 offset:8192
	s_waitcnt lgkmcnt(6)
	v_mfma_f32_32x32x16_bf16 v[162:177], v[202:205], v[238:241], v[162:177]
	s_waitcnt lgkmcnt(5)
	v_mfma_f32_32x32x16_bf16 v[146:161], v[206:209], v[238:241], v[146:161]
	ds_read_b128 v[238:241], v227 offset:12288
	s_waitcnt lgkmcnt(4)
	v_mfma_f32_32x32x16_bf16 v[194:209], v[250:253], v[246:249], 0
	s_waitcnt lgkmcnt(3)
	v_mfma_f32_32x32x16_bf16 v[178:193], v[6:9], v[246:249], 0
	ds_read_b128 v[246:249], v236 offset:192
	ds_read_b128 v[250:253], v228 offset:8192
	ds_read_b128 v[6:9], v228 offset:12288
	s_waitcnt lgkmcnt(4)
	v_mfma_f32_32x32x16_bf16 v[194:209], v[14:17], v[10:13], v[194:209]
	s_waitcnt lgkmcnt(3)
	v_mfma_f32_32x32x16_bf16 v[178:193], v[238:241], v[10:13], v[178:193]
	ds_read_b128 v[10:13], v236 offset:224
	ds_read_b128 v[14:17], v230 offset:8192
	ds_read_b128 v[238:241], v230 offset:12288
	s_waitcnt lgkmcnt(4)
	v_mfma_f32_32x32x16_bf16 v[194:209], v[250:253], v[246:249], v[194:209]
	s_waitcnt lgkmcnt(3)
	v_mfma_f32_32x32x16_bf16 v[178:193], v[6:9], v[246:249], v[178:193]
	s_waitcnt lgkmcnt(1)
	v_mfma_f32_32x32x16_bf16 v[194:209], v[14:17], v[10:13], v[194:209]
	s_waitcnt lgkmcnt(0)
	v_mfma_f32_32x32x16_bf16 v[178:193], v[238:241], v[10:13], v[178:193]
	ds_read_b64_tr_b16 v[10:11], v231 offset:16384
	ds_read_b64_tr_b16 v[12:13], v231 offset:18432
	v_exp_f32_e32 v166, v166
	v_exp_f32_e32 v167, v167
	v_exp_f32_e32 v168, v168
	v_exp_f32_e32 v169, v169
	v_exp_f32_e32 v240, v162
	v_exp_f32_e32 v237, v163
	v_exp_f32_e32 v238, v164
	v_exp_f32_e32 v239, v165
	ds_read_b64_tr_b16 v[162:163], v232 offset:16384
	ds_read_b64_tr_b16 v[164:165], v232 offset:18432
	v_cvt_pk_bf16_f32 v6, v240, v237
	v_cvt_pk_bf16_f32 v7, v238, v239
	v_cvt_pk_bf16_f32 v8, v166, v167
	v_cvt_pk_bf16_f32 v9, v168, v169
	v_exp_f32_e32 v2, v194
	s_waitcnt lgkmcnt(2)
	v_mfma_f32_32x32x16_bf16 v[82:97], v[6:9], v[10:13], v[82:97]
	v_exp_f32_e32 v194, v195
	v_exp_f32_e32 v195, v196
	v_exp_f32_e32 v196, v197
	v_exp_f32_e32 v197, v198
	v_exp_f32_e32 v198, v199
	v_exp_f32_e32 v199, v200
	v_exp_f32_e32 v200, v201
	v_cvt_pk_bf16_f32 v14, v2, v194
	v_cvt_pk_bf16_f32 v15, v195, v196
	v_cvt_pk_bf16_f32 v16, v197, v198
	v_cvt_pk_bf16_f32 v17, v199, v200
	v_exp_f32_e32 v202, v202
	v_exp_f32_e32 v203, v203
	v_mfma_f32_32x32x16_bf16 v[130:145], v[14:17], v[10:13], v[130:145]
	v_exp_f32_e32 v204, v204
	v_exp_f32_e32 v205, v205
	v_exp_f32_e32 v206, v206
	v_exp_f32_e32 v207, v207
	v_exp_f32_e32 v208, v208
	ds_read_b64_tr_b16 v[10:11], v233 offset:16384
	ds_read_b64_tr_b16 v[12:13], v233 offset:18432
	v_exp_f32_e32 v170, v170
	v_exp_f32_e32 v171, v171
	v_exp_f32_e32 v172, v172
	v_exp_f32_e32 v173, v173
	v_exp_f32_e32 v174, v174
	v_exp_f32_e32 v175, v175
	s_waitcnt lgkmcnt(2)
	v_mfma_f32_32x32x16_bf16 v[66:81], v[6:9], v[162:165], v[66:81]
	v_exp_f32_e32 v176, v176
	v_exp_f32_e32 v177, v177
	v_exp_f32_e32 v209, v209
	v_exp_f32_e32 v178, v178
	v_exp_f32_e32 v179, v179
	v_exp_f32_e32 v180, v180
	v_exp_f32_e32 v181, v181
	v_mfma_f32_32x32x16_bf16 v[114:129], v[14:17], v[162:165], v[114:129]
	ds_read_b64_tr_b16 v[162:163], v234 offset:16384
	ds_read_b64_tr_b16 v[164:165], v234 offset:18432
	v_add_f32_e32 v2, v178, v2
	v_add_f32_e32 v2, 0, v2
	v_add_f32_e32 v194, v179, v194
	v_add_f32_e32 v2, v194, v2
	v_add_f32_e32 v194, v180, v195
	s_waitcnt lgkmcnt(2)
	v_mfma_f32_32x32x16_bf16 v[34:49], v[6:9], v[10:13], v[34:49]
	v_add_f32_e32 v2, v194, v2
	v_add_f32_e32 v194, v181, v196
	v_add_f32_e32 v2, v194, v2
	v_exp_f32_e32 v182, v182
	v_exp_f32_e32 v183, v183
	v_exp_f32_e32 v184, v184
	v_exp_f32_e32 v194, v146
	v_mfma_f32_32x32x16_bf16 v[98:113], v[14:17], v[10:13], v[98:113]
	ds_read_b64_tr_b16 v[10:11], v231 offset:20480
	ds_read_b64_tr_b16 v[12:13], v231 offset:22528
	v_exp_f32_e32 v195, v147
	v_exp_f32_e32 v196, v148
	v_exp_f32_e32 v244, v149
	v_exp_f32_e32 v150, v150
	v_exp_f32_e32 v151, v151
	v_exp_f32_e32 v152, v152
	s_waitcnt lgkmcnt(2)
	v_mfma_f32_32x32x16_bf16 v[18:33], v[6:9], v[162:165], v[18:33]
	v_cvt_pk_bf16_f32 v6, v170, v171
	v_cvt_pk_bf16_f32 v7, v172, v173
	v_cvt_pk_bf16_f32 v8, v174, v175
	v_cvt_pk_bf16_f32 v9, v176, v177
	v_exp_f32_e32 v153, v153
	v_exp_f32_e32 v154, v154
	v_exp_f32_e32 v155, v155
	v_mfma_f32_32x32x16_bf16 v[50:65], v[14:17], v[162:165], v[50:65]
	v_cvt_pk_bf16_f32 v14, v202, v203
	ds_read_b64_tr_b16 v[162:163], v232 offset:20480
	ds_read_b64_tr_b16 v[164:165], v232 offset:22528
	v_cvt_pk_bf16_f32 v15, v204, v205
	v_cvt_pk_bf16_f32 v16, v206, v207
	v_cvt_pk_bf16_f32 v17, v208, v209
	v_exp_f32_e32 v156, v156
	s_waitcnt lgkmcnt(2)
	v_mfma_f32_32x32x16_bf16 v[82:97], v[6:9], v[10:13], v[82:97]
	v_exp_f32_e32 v157, v157
	v_exp_f32_e32 v158, v158
	v_exp_f32_e32 v159, v159
	v_exp_f32_e32 v160, v160
	v_exp_f32_e32 v161, v161
	s_add_u32 s42, s42, 0xa8000
	s_addc_u32 s43, s43, 0
	v_mfma_f32_32x32x16_bf16 v[130:145], v[14:17], v[10:13], v[130:145]
	ds_read_b64_tr_b16 v[10:11], v233 offset:20480
	ds_read_b64_tr_b16 v[12:13], v233 offset:22528
	s_waitcnt lgkmcnt(2)
	v_mfma_f32_32x32x16_bf16 v[66:81], v[6:9], v[162:165], v[66:81]
	v_mfma_f32_32x32x16_bf16 v[114:129], v[14:17], v[162:165], v[114:129]
	ds_read_b64_tr_b16 v[162:163], v234 offset:20480
	ds_read_b64_tr_b16 v[164:165], v234 offset:22528
	s_waitcnt lgkmcnt(0)
	v_mfma_f32_32x32x16_bf16 v[18:33], v[6:9], v[162:165], v[18:33]
	v_mfma_f32_32x32x16_bf16 v[50:65], v[14:17], v[162:165], v[50:65]
	v_exp_f32_e32 v162, v185
	v_add_f32_e32 v163, v182, v197
	v_add_f32_e32 v2, v163, v2
	v_add_f32_e32 v163, v183, v198
	v_add_f32_e32 v2, v163, v2
	v_exp_f32_e32 v163, v186
	v_exp_f32_e32 v164, v188
	v_mfma_f32_32x32x16_bf16 v[34:49], v[6:9], v[10:13], v[34:49]
	v_cvt_pk_bf16_f32 v6, v194, v195
	v_cvt_pk_bf16_f32 v7, v196, v244
	v_cvt_pk_bf16_f32 v8, v150, v151
	v_cvt_pk_bf16_f32 v9, v152, v153
	v_exp_f32_e32 v165, v189
	v_mfma_f32_32x32x16_bf16 v[98:113], v[14:17], v[10:13], v[98:113]
	ds_read_b64_tr_b16 v[10:11], v231 offset:24576
	ds_read_b64_tr_b16 v[12:13], v231 offset:26624
	v_cvt_pk_bf16_f32 v14, v178, v179
	v_cvt_pk_bf16_f32 v15, v180, v181
	v_cvt_pk_bf16_f32 v16, v182, v183
	v_cvt_pk_bf16_f32 v17, v184, v162
	ds_read_b64_tr_b16 v[146:147], v232 offset:24576
	ds_read_b64_tr_b16 v[148:149], v232 offset:26624
	v_add_f32_e32 v178, v165, v205
	s_waitcnt lgkmcnt(2)
	v_mfma_f32_32x32x16_bf16 v[82:97], v[6:9], v[10:13], v[82:97]
	v_exp_f32_e32 v179, v190
	s_nop 0
	v_add_f32_e32 v180, v179, v206
	v_mfma_f32_32x32x16_bf16 v[130:145], v[14:17], v[10:13], v[130:145]
	v_add_f32_e32 v10, v184, v199
	v_add_f32_e32 v2, v10, v2
	v_add_f32_e32 v10, v162, v200
	v_exp_f32_e32 v162, v187
	v_add_f32_e32 v2, v10, v2
	v_add_f32_e32 v10, v163, v202
	v_add_f32_e32 v2, v10, v2
	v_add_f32_e32 v10, v162, v203
	v_add_f32_e32 v2, v10, v2
	v_add_f32_e32 v10, v164, v204
	v_add_f32_e32 v2, v10, v2
	v_add_f32_e32 v2, v178, v2
	v_exp_f32_e32 v178, v191
	ds_read_b64_tr_b16 v[10:11], v233 offset:24576
	ds_read_b64_tr_b16 v[12:13], v233 offset:26624
	s_waitcnt lgkmcnt(2)
	v_mfma_f32_32x32x16_bf16 v[66:81], v[6:9], v[146:149], v[66:81]
	v_add_f32_e32 v2, v180, v2
	v_exp_f32_e32 v180, v192
	v_add_f32_e32 v181, v178, v207
	v_add_f32_e32 v2, v181, v2
	v_exp_f32_e32 v181, v193
	v_mfma_f32_32x32x16_bf16 v[114:129], v[14:17], v[146:149], v[114:129]
	ds_read_b64_tr_b16 v[146:147], v234 offset:24576
	ds_read_b64_tr_b16 v[148:149], v234 offset:26624
	s_waitcnt lgkmcnt(2)
	v_mfma_f32_32x32x16_bf16 v[34:49], v[6:9], v[10:13], v[34:49]
	v_mfma_f32_32x32x16_bf16 v[98:113], v[14:17], v[10:13], v[98:113]
	v_add_f32_e32 v10, v180, v208
	v_add_f32_e32 v2, v10, v2
	ds_read_b64_tr_b16 v[10:11], v231 offset:28672
	ds_read_b64_tr_b16 v[12:13], v231 offset:30720
	s_waitcnt lgkmcnt(2)
	v_mfma_f32_32x32x16_bf16 v[18:33], v[6:9], v[146:149], v[18:33]
	v_cvt_pk_bf16_f32 v6, v154, v155
	v_cvt_pk_bf16_f32 v7, v156, v157
	v_cvt_pk_bf16_f32 v8, v158, v159
	v_cvt_pk_bf16_f32 v9, v160, v161
	v_mfma_f32_32x32x16_bf16 v[50:65], v[14:17], v[146:149], v[50:65]
	v_cvt_pk_bf16_f32 v14, v163, v162
	v_cvt_pk_bf16_f32 v15, v164, v165
	v_cvt_pk_bf16_f32 v16, v179, v178
	v_cvt_pk_bf16_f32 v17, v180, v181
	v_add_f32_e32 v162, v181, v209
	v_add_f32_e32 v2, v162, v2
	v_add_f32_e32 v4, v4, v2
	v_add_f32_e32 v2, v194, v240
	s_waitcnt lgkmcnt(0)
	v_mfma_f32_32x32x16_bf16 v[82:97], v[6:9], v[10:13], v[82:97]
	v_add_f32_e32 v2, 0, v2
	ds_read_b64_tr_b16 v[146:147], v232 offset:28672
	ds_read_b64_tr_b16 v[148:149], v232 offset:30720
	v_mfma_f32_32x32x16_bf16 v[130:145], v[14:17], v[10:13], v[130:145]
	v_add_f32_e32 v10, v195, v237
	v_add_f32_e32 v2, v10, v2
	v_add_f32_e32 v10, v196, v238
	v_add_f32_e32 v2, v10, v2
	v_add_f32_e32 v10, v244, v239
	v_add_f32_e32 v2, v10, v2
	v_add_f32_e32 v10, v150, v166
	v_add_f32_e32 v2, v10, v2
	v_add_f32_e32 v10, v151, v167
	v_add_f32_e32 v2, v10, v2
	v_add_f32_e32 v10, v152, v168
	s_waitcnt lgkmcnt(0)
	v_mfma_f32_32x32x16_bf16 v[66:81], v[6:9], v[146:149], v[66:81]
	v_add_f32_e32 v2, v10, v2
	ds_read_b64_tr_b16 v[10:11], v233 offset:28672
	ds_read_b64_tr_b16 v[12:13], v233 offset:30720
	v_add_f32_e32 v150, v153, v169
	v_add_f32_e32 v2, v150, v2
	v_add_f32_e32 v150, v154, v170
	v_add_f32_e32 v2, v150, v2
	v_add_f32_e32 v150, v155, v171
	v_mfma_f32_32x32x16_bf16 v[114:129], v[14:17], v[146:149], v[114:129]
	ds_read_b64_tr_b16 v[146:147], v234 offset:28672
	ds_read_b64_tr_b16 v[148:149], v234 offset:30720
	v_add_f32_e32 v2, v150, v2
	v_add_f32_e32 v150, v156, v172
	v_add_f32_e32 v2, v150, v2
	v_add_f32_e32 v150, v157, v173
	v_add_f32_e32 v2, v150, v2
	s_waitcnt lgkmcnt(2)
	v_mfma_f32_32x32x16_bf16 v[34:49], v[6:9], v[10:13], v[34:49]
	v_mfma_f32_32x32x16_bf16 v[98:113], v[14:17], v[10:13], v[98:113]
	v_add_f32_e32 v10, v158, v174
	v_add_f32_e32 v2, v10, v2
	v_add_f32_e32 v10, v159, v175
	v_add_f32_e32 v2, v10, v2
	v_add_f32_e32 v10, v160, v176
	v_add_f32_e32 v2, v10, v2
	v_add_f32_e32 v10, v161, v177
	s_waitcnt lgkmcnt(0)
	v_mfma_f32_32x32x16_bf16 v[18:33], v[6:9], v[146:149], v[18:33]
	v_add_f32_e32 v2, v10, v2
	v_add_f32_e32 v235, v235, v2
	v_mfma_f32_32x32x16_bf16 v[50:65], v[14:17], v[146:149], v[50:65]
	s_waitcnt vmcnt(0)
	s_barrier
	s_cmp_eq_u32 s42, 0x5358000
	s_cbranch_scc1 .Lfast_skip_dma
	s_add_u32 s80, s74, s42
	s_addc_u32 s81, s75, s43
	s_add_i32 s4, s55, 0
	s_mov_b32 m0, s4
	s_add_u32 s82, s76, s42
	s_addc_u32 s83, s77, s43
	global_load_lds_dwordx4 v254, s[80:81]
	s_add_i32 m0, s4, 0x1f80
	s_add_u32 s84, s82, 0x54000
	s_addc_u32 s85, s83, 0
	global_load_lds_dwordx4 v254, s[80:81] offset:128
	s_add_i32 m0, s4, 0x4000
	s_nop 0
	global_load_lds_dwordx4 v255, s[82:83]
	s_add_i32 m0, s4, 0x6000
	s_nop 0
	global_load_lds_dwordx4 v255, s[84:85]
.Lfast_skip_dma:
	ds_read_b128 v[6:9], v236
	ds_read_b128 v[178:181], v226 offset:32768
	ds_read_b128 v[182:185], v226 offset:36864
	ds_read_b128 v[10:13], v236 offset:32
	ds_read_b128 v[186:189], v227 offset:32768
	ds_read_b128 v[190:193], v227 offset:36864
	ds_read_b128 v[14:17], v236 offset:64
	ds_read_b128 v[194:197], v228 offset:32768
	ds_read_b128 v[198:201], v228 offset:36864
	ds_read_b128 v[238:241], v236 offset:96
	ds_read_b128 v[202:205], v230 offset:32768
	ds_read_b128 v[206:209], v230 offset:36864
	s_waitcnt lgkmcnt(10)
	v_mfma_f32_32x32x16_bf16 v[162:177], v[178:181], v[6:9], 0
	s_waitcnt lgkmcnt(9)
	v_mfma_f32_32x32x16_bf16 v[146:161], v[182:185], v[6:9], 0
	ds_read_b128 v[246:249], v236 offset:128
	ds_read_b128 v[250:253], v226 offset:40960
	ds_read_b128 v[6:9], v226 offset:45056
	s_waitcnt lgkmcnt(10)
	v_mfma_f32_32x32x16_bf16 v[162:177], v[186:189], v[10:13], v[162:177]
	s_waitcnt lgkmcnt(9)
	v_mfma_f32_32x32x16_bf16 v[146:161], v[190:193], v[10:13], v[146:161]
	ds_read_b128 v[10:13], v236 offset:160
	s_waitcnt lgkmcnt(8)
	v_mfma_f32_32x32x16_bf16 v[162:177], v[194:197], v[14:17], v[162:177]
	s_waitcnt lgkmcnt(7)
	v_mfma_f32_32x32x16_bf16 v[146:161], v[198:201], v[14:17], v[146:161]
	ds_read_b128 v[14:17], v227 offset:40960
	s_waitcnt lgkmcnt(6)
	v_mfma_f32_32x32x16_bf16 v[162:177], v[202:205], v[238:241], v[162:177]
	s_waitcnt lgkmcnt(5)
	v_mfma_f32_32x32x16_bf16 v[146:161], v[206:209], v[238:241], v[146:161]
	ds_read_b128 v[238:241], v227 offset:45056
	s_waitcnt lgkmcnt(4)
	v_mfma_f32_32x32x16_bf16 v[194:209], v[250:253], v[246:249], 0
	s_waitcnt lgkmcnt(3)
	v_mfma_f32_32x32x16_bf16 v[178:193], v[6:9], v[246:249], 0
	ds_read_b128 v[246:249], v236 offset:192
	ds_read_b128 v[250:253], v228 offset:40960
	ds_read_b128 v[6:9], v228 offset:45056
	s_waitcnt lgkmcnt(4)
	v_mfma_f32_32x32x16_bf16 v[194:209], v[14:17], v[10:13], v[194:209]
	s_waitcnt lgkmcnt(3)
	v_mfma_f32_32x32x16_bf16 v[178:193], v[238:241], v[10:13], v[178:193]
	ds_read_b128 v[10:13], v236 offset:224
	ds_read_b128 v[14:17], v230 offset:40960
	ds_read_b128 v[238:241], v230 offset:45056
	s_waitcnt lgkmcnt(4)
	v_mfma_f32_32x32x16_bf16 v[194:209], v[250:253], v[246:249], v[194:209]
	s_waitcnt lgkmcnt(3)
	v_mfma_f32_32x32x16_bf16 v[178:193], v[6:9], v[246:249], v[178:193]
	s_waitcnt lgkmcnt(1)
	v_mfma_f32_32x32x16_bf16 v[194:209], v[14:17], v[10:13], v[194:209]
	s_waitcnt lgkmcnt(0)
	v_mfma_f32_32x32x16_bf16 v[178:193], v[238:241], v[10:13], v[178:193]
	ds_read_b64_tr_b16 v[10:11], v231 offset:49152
	ds_read_b64_tr_b16 v[12:13], v231 offset:51200
	v_exp_f32_e32 v166, v166
	v_exp_f32_e32 v167, v167
	v_exp_f32_e32 v168, v168
	v_exp_f32_e32 v169, v169
	v_exp_f32_e32 v240, v162
	v_exp_f32_e32 v237, v163
	v_exp_f32_e32 v238, v164
	v_exp_f32_e32 v239, v165
	ds_read_b64_tr_b16 v[162:163], v232 offset:49152
	ds_read_b64_tr_b16 v[164:165], v232 offset:51200
	v_cvt_pk_bf16_f32 v6, v240, v237
	v_cvt_pk_bf16_f32 v7, v238, v239
	v_cvt_pk_bf16_f32 v8, v166, v167
	v_cvt_pk_bf16_f32 v9, v168, v169
	v_exp_f32_e32 v2, v194
	s_waitcnt lgkmcnt(2)
	v_mfma_f32_32x32x16_bf16 v[82:97], v[6:9], v[10:13], v[82:97]
	v_exp_f32_e32 v194, v195
	v_exp_f32_e32 v195, v196
	v_exp_f32_e32 v196, v197
	v_exp_f32_e32 v197, v198
	v_exp_f32_e32 v198, v199
	v_exp_f32_e32 v199, v200
	v_exp_f32_e32 v200, v201
	v_cvt_pk_bf16_f32 v14, v2, v194
	v_cvt_pk_bf16_f32 v15, v195, v196
	v_cvt_pk_bf16_f32 v16, v197, v198
	v_cvt_pk_bf16_f32 v17, v199, v200
	v_exp_f32_e32 v202, v202
	v_exp_f32_e32 v203, v203
	v_mfma_f32_32x32x16_bf16 v[130:145], v[14:17], v[10:13], v[130:145]
	v_exp_f32_e32 v204, v204
	v_exp_f32_e32 v205, v205
	v_exp_f32_e32 v206, v206
	v_exp_f32_e32 v207, v207
	v_exp_f32_e32 v208, v208
	ds_read_b64_tr_b16 v[10:11], v233 offset:49152
	ds_read_b64_tr_b16 v[12:13], v233 offset:51200
	v_exp_f32_e32 v170, v170
	v_exp_f32_e32 v171, v171
	v_exp_f32_e32 v172, v172
	v_exp_f32_e32 v173, v173
	v_exp_f32_e32 v174, v174
	v_exp_f32_e32 v175, v175
	s_waitcnt lgkmcnt(2)
	v_mfma_f32_32x32x16_bf16 v[66:81], v[6:9], v[162:165], v[66:81]
	v_exp_f32_e32 v176, v176
	v_exp_f32_e32 v177, v177
	v_exp_f32_e32 v209, v209
	v_exp_f32_e32 v178, v178
	v_exp_f32_e32 v179, v179
	v_exp_f32_e32 v180, v180
	v_exp_f32_e32 v181, v181
	v_mfma_f32_32x32x16_bf16 v[114:129], v[14:17], v[162:165], v[114:129]
	ds_read_b64_tr_b16 v[162:163], v234 offset:49152
	ds_read_b64_tr_b16 v[164:165], v234 offset:51200
	v_add_f32_e32 v2, v178, v2
	v_add_f32_e32 v2, 0, v2
	v_add_f32_e32 v194, v179, v194
	v_add_f32_e32 v2, v194, v2
	v_add_f32_e32 v194, v180, v195
	s_waitcnt lgkmcnt(2)
	v_mfma_f32_32x32x16_bf16 v[34:49], v[6:9], v[10:13], v[34:49]
	v_add_f32_e32 v2, v194, v2
	v_add_f32_e32 v194, v181, v196
	v_add_f32_e32 v2, v194, v2
	v_exp_f32_e32 v182, v182
	v_exp_f32_e32 v183, v183
	v_exp_f32_e32 v184, v184
	v_exp_f32_e32 v194, v146
	v_mfma_f32_32x32x16_bf16 v[98:113], v[14:17], v[10:13], v[98:113]
	ds_read_b64_tr_b16 v[10:11], v231 offset:53248
	ds_read_b64_tr_b16 v[12:13], v231 offset:55296
	v_exp_f32_e32 v195, v147
	v_exp_f32_e32 v196, v148
	v_exp_f32_e32 v244, v149
	v_exp_f32_e32 v150, v150
	v_exp_f32_e32 v151, v151
	v_exp_f32_e32 v152, v152
	s_waitcnt lgkmcnt(2)
	v_mfma_f32_32x32x16_bf16 v[18:33], v[6:9], v[162:165], v[18:33]
	v_cvt_pk_bf16_f32 v6, v170, v171
	v_cvt_pk_bf16_f32 v7, v172, v173
	v_cvt_pk_bf16_f32 v8, v174, v175
	v_cvt_pk_bf16_f32 v9, v176, v177
	v_exp_f32_e32 v153, v153
	v_exp_f32_e32 v154, v154
	v_exp_f32_e32 v155, v155
	v_mfma_f32_32x32x16_bf16 v[50:65], v[14:17], v[162:165], v[50:65]
	v_cvt_pk_bf16_f32 v14, v202, v203
	ds_read_b64_tr_b16 v[162:163], v232 offset:53248
	ds_read_b64_tr_b16 v[164:165], v232 offset:55296
	v_cvt_pk_bf16_f32 v15, v204, v205
	v_cvt_pk_bf16_f32 v16, v206, v207
	v_cvt_pk_bf16_f32 v17, v208, v209
	v_exp_f32_e32 v156, v156
	s_waitcnt lgkmcnt(2)
	v_mfma_f32_32x32x16_bf16 v[82:97], v[6:9], v[10:13], v[82:97]
	v_exp_f32_e32 v157, v157
	v_exp_f32_e32 v158, v158
	v_exp_f32_e32 v159, v159
	v_exp_f32_e32 v160, v160
	v_exp_f32_e32 v161, v161
	s_add_u32 s42, s42, 0xa8000
	s_addc_u32 s43, s43, 0
	v_mfma_f32_32x32x16_bf16 v[130:145], v[14:17], v[10:13], v[130:145]
	ds_read_b64_tr_b16 v[10:11], v233 offset:53248
	ds_read_b64_tr_b16 v[12:13], v233 offset:55296
	s_cmp_eq_u32 s42, 0x5400000
	s_waitcnt lgkmcnt(2)
	v_mfma_f32_32x32x16_bf16 v[66:81], v[6:9], v[162:165], v[66:81]
	v_mfma_f32_32x32x16_bf16 v[114:129], v[14:17], v[162:165], v[114:129]
	ds_read_b64_tr_b16 v[162:163], v234 offset:53248
	ds_read_b64_tr_b16 v[164:165], v234 offset:55296
	s_waitcnt lgkmcnt(0)
	v_mfma_f32_32x32x16_bf16 v[18:33], v[6:9], v[162:165], v[18:33]
	v_mfma_f32_32x32x16_bf16 v[50:65], v[14:17], v[162:165], v[50:65]
	v_exp_f32_e32 v162, v185
	v_add_f32_e32 v163, v182, v197
	v_add_f32_e32 v2, v163, v2
	v_add_f32_e32 v163, v183, v198
	v_add_f32_e32 v2, v163, v2
	v_exp_f32_e32 v163, v186
	v_exp_f32_e32 v164, v188
	v_mfma_f32_32x32x16_bf16 v[34:49], v[6:9], v[10:13], v[34:49]
	v_cvt_pk_bf16_f32 v6, v194, v195
	v_cvt_pk_bf16_f32 v7, v196, v244
	v_cvt_pk_bf16_f32 v8, v150, v151
	v_cvt_pk_bf16_f32 v9, v152, v153
	v_exp_f32_e32 v165, v189
	v_mfma_f32_32x32x16_bf16 v[98:113], v[14:17], v[10:13], v[98:113]
	ds_read_b64_tr_b16 v[10:11], v231 offset:57344
	ds_read_b64_tr_b16 v[12:13], v231 offset:59392
	v_cvt_pk_bf16_f32 v14, v178, v179
	v_cvt_pk_bf16_f32 v15, v180, v181
	v_cvt_pk_bf16_f32 v16, v182, v183
	v_cvt_pk_bf16_f32 v17, v184, v162
	ds_read_b64_tr_b16 v[146:147], v232 offset:57344
	ds_read_b64_tr_b16 v[148:149], v232 offset:59392
	v_add_f32_e32 v178, v165, v205
	s_waitcnt lgkmcnt(2)
	v_mfma_f32_32x32x16_bf16 v[82:97], v[6:9], v[10:13], v[82:97]
	v_exp_f32_e32 v179, v190
	s_nop 0
	v_add_f32_e32 v180, v179, v206
	v_mfma_f32_32x32x16_bf16 v[130:145], v[14:17], v[10:13], v[130:145]
	v_add_f32_e32 v10, v184, v199
	v_add_f32_e32 v2, v10, v2
	v_add_f32_e32 v10, v162, v200
	v_exp_f32_e32 v162, v187
	v_add_f32_e32 v2, v10, v2
	v_add_f32_e32 v10, v163, v202
	v_add_f32_e32 v2, v10, v2
	v_add_f32_e32 v10, v162, v203
	v_add_f32_e32 v2, v10, v2
	v_add_f32_e32 v10, v164, v204
	v_add_f32_e32 v2, v10, v2
	v_add_f32_e32 v2, v178, v2
	v_exp_f32_e32 v178, v191
	ds_read_b64_tr_b16 v[10:11], v233 offset:57344
	ds_read_b64_tr_b16 v[12:13], v233 offset:59392
	s_waitcnt lgkmcnt(2)
	v_mfma_f32_32x32x16_bf16 v[66:81], v[6:9], v[146:149], v[66:81]
	v_add_f32_e32 v2, v180, v2
	v_exp_f32_e32 v180, v192
	v_add_f32_e32 v181, v178, v207
	v_add_f32_e32 v2, v181, v2
	v_exp_f32_e32 v181, v193
	v_mfma_f32_32x32x16_bf16 v[114:129], v[14:17], v[146:149], v[114:129]
	ds_read_b64_tr_b16 v[146:147], v234 offset:57344
	ds_read_b64_tr_b16 v[148:149], v234 offset:59392
	s_waitcnt lgkmcnt(2)
	v_mfma_f32_32x32x16_bf16 v[34:49], v[6:9], v[10:13], v[34:49]
	v_mfma_f32_32x32x16_bf16 v[98:113], v[14:17], v[10:13], v[98:113]
	v_add_f32_e32 v10, v180, v208
	v_add_f32_e32 v2, v10, v2
	ds_read_b64_tr_b16 v[10:11], v231 offset:61440
	ds_read_b64_tr_b16 v[12:13], v231 offset:63488
	s_waitcnt lgkmcnt(2)
	v_mfma_f32_32x32x16_bf16 v[18:33], v[6:9], v[146:149], v[18:33]
	v_cvt_pk_bf16_f32 v6, v154, v155
	v_cvt_pk_bf16_f32 v7, v156, v157
	v_cvt_pk_bf16_f32 v8, v158, v159
	v_cvt_pk_bf16_f32 v9, v160, v161
	v_mfma_f32_32x32x16_bf16 v[50:65], v[14:17], v[146:149], v[50:65]
	v_cvt_pk_bf16_f32 v14, v163, v162
	v_cvt_pk_bf16_f32 v15, v164, v165
	v_cvt_pk_bf16_f32 v16, v179, v178
	v_cvt_pk_bf16_f32 v17, v180, v181
	v_add_f32_e32 v162, v181, v209
	v_add_f32_e32 v2, v162, v2
	v_add_f32_e32 v4, v4, v2
	v_add_f32_e32 v2, v194, v240
	s_waitcnt lgkmcnt(0)
	v_mfma_f32_32x32x16_bf16 v[82:97], v[6:9], v[10:13], v[82:97]
	v_add_f32_e32 v2, 0, v2
	ds_read_b64_tr_b16 v[146:147], v232 offset:61440
	ds_read_b64_tr_b16 v[148:149], v232 offset:63488
	v_mfma_f32_32x32x16_bf16 v[130:145], v[14:17], v[10:13], v[130:145]
	v_add_f32_e32 v10, v195, v237
	v_add_f32_e32 v2, v10, v2
	v_add_f32_e32 v10, v196, v238
	v_add_f32_e32 v2, v10, v2
	v_add_f32_e32 v10, v244, v239
	v_add_f32_e32 v2, v10, v2
	v_add_f32_e32 v10, v150, v166
	v_add_f32_e32 v2, v10, v2
	v_add_f32_e32 v10, v151, v167
	v_add_f32_e32 v2, v10, v2
	v_add_f32_e32 v10, v152, v168
	s_waitcnt lgkmcnt(0)
	v_mfma_f32_32x32x16_bf16 v[66:81], v[6:9], v[146:149], v[66:81]
	v_add_f32_e32 v2, v10, v2
	ds_read_b64_tr_b16 v[10:11], v233 offset:61440
	ds_read_b64_tr_b16 v[12:13], v233 offset:63488
	v_add_f32_e32 v150, v153, v169
	v_add_f32_e32 v2, v150, v2
	v_add_f32_e32 v150, v154, v170
	v_add_f32_e32 v2, v150, v2
	v_add_f32_e32 v150, v155, v171
	v_mfma_f32_32x32x16_bf16 v[114:129], v[14:17], v[146:149], v[114:129]
	ds_read_b64_tr_b16 v[146:147], v234 offset:61440
	ds_read_b64_tr_b16 v[148:149], v234 offset:63488
	v_add_f32_e32 v2, v150, v2
	v_add_f32_e32 v150, v156, v172
	v_add_f32_e32 v2, v150, v2
	v_add_f32_e32 v150, v157, v173
	v_add_f32_e32 v2, v150, v2
	s_waitcnt lgkmcnt(2)
	v_mfma_f32_32x32x16_bf16 v[34:49], v[6:9], v[10:13], v[34:49]
	v_mfma_f32_32x32x16_bf16 v[98:113], v[14:17], v[10:13], v[98:113]
	v_add_f32_e32 v10, v158, v174
	v_add_f32_e32 v2, v10, v2
	v_add_f32_e32 v10, v159, v175
	v_add_f32_e32 v2, v10, v2
	v_add_f32_e32 v10, v160, v176
	v_add_f32_e32 v2, v10, v2
	v_add_f32_e32 v10, v161, v177
	s_waitcnt lgkmcnt(0)
	v_mfma_f32_32x32x16_bf16 v[18:33], v[6:9], v[146:149], v[18:33]
	v_add_f32_e32 v2, v10, v2
	v_add_f32_e32 v235, v235, v2
	v_mfma_f32_32x32x16_bf16 v[50:65], v[14:17], v[146:149], v[50:65]
	s_cbranch_scc0 .Lfast_loop
